# v030 + waves 0-3 keep priority 1 for the whole attention loop after their first QK block (in-loop s_setprio 0 removed)
# baseline (speedup 1.0000x reference)
; #define LAS __attribute__((address_space(3)))
; template <bool HAS_POST, class MaskF>
; __device__ __forceinline__ void attn_run(LAS unsigned char* lds, const bf16* Kg, const bf16* Vg, int pitch, int t0, int t1,
;                                          const bf16x8 (&qr)[4], f32x16& o0, f32x16& o1, f32x16& o2, MaskF& mf, const int wv) {
;     ...
;             if (wv < 4) __builtin_amdgcn_s_setprio(1);
; #pragma unroll
;             for (int d0 = 0; d0 < 4; ++d0) {
;                 const bf16x8 a0 = *(const LAS bf16x8*)(Kb + d0 * 32), a1 = *(const LAS bf16x8*)(Kb + 32 * 144 + d0 * 32);
;                 if (d0 == 0) { p0 = __builtin_amdgcn_mfma_f32_32x32x16_bf16(a0, qr[0], zc, 0, 0, 0); p1 = __builtin_amdgcn_mfma_f32_32x32x16_bf16(a1, qr[0], zc, 0, 0, 0); }
;                 else { p0 = __builtin_amdgcn_mfma_f32_32x32x16_bf16(a0, qr[d0], p0, 0, 0, 0); p1 = __builtin_amdgcn_mfma_f32_32x32x16_bf16(a1, qr[d0], p1, 0, 0, 0); }
;             }
;             if (wv < 4) __builtin_amdgcn_s_setprio(0);
.LBB0_858:
	s_and_b64 vcc, exec, s[8:9]
	s_waitcnt lgkmcnt(7)
	v_mfma_f32_32x32x16_bf16 v[66:81], v[102:105], v[116:119], 0
	s_waitcnt lgkmcnt(6)
	v_mfma_f32_32x32x16_bf16 v[66:81], v[110:113], v[120:123], v[66:81]
	s_waitcnt lgkmcnt(5)
	v_mfma_f32_32x32x16_bf16 v[50:65], v[50:53], v[116:119], 0
	s_waitcnt lgkmcnt(4)
	v_mfma_f32_32x32x16_bf16 v[50:65], v[132:135], v[120:123], v[50:65]
	s_waitcnt lgkmcnt(3)
	v_mfma_f32_32x32x16_bf16 v[66:81], v[136:139], v[124:127], v[66:81]
	s_waitcnt lgkmcnt(2)
	v_mfma_f32_32x32x16_bf16 v[50:65], v[140:143], v[124:127], v[50:65]
	s_waitcnt lgkmcnt(1)
	v_mfma_f32_32x32x16_bf16 v[66:81], v[144:147], v[128:131], v[66:81]
	s_waitcnt lgkmcnt(0)
	v_mfma_f32_32x32x16_bf16 v[50:65], v[148:151], v[128:131], v[50:65]
	s_cbranch_vccnz .LBB0_860
	s_nop 0

; #define LAS __attribute__((address_space(3)))
; template <bool HAS_POST, class MaskF>
; __device__ __forceinline__ void attn_run(LAS unsigned char* lds, const bf16* Kg, const bf16* Vg, int pitch, int t0, int t1,
;                                          const bf16x8 (&qr)[4], f32x16& o0, f32x16& o1, f32x16& o2, MaskF& mf, const int wv) {
;     ...
;             if (wv < 4) __builtin_amdgcn_s_setprio(1);
; #pragma unroll
;             for (int d0 = 0; d0 < 4; ++d0) {
;                 const bf16x8 a0 = *(const LAS bf16x8*)(Kb + d0 * 32), a1 = *(const LAS bf16x8*)(Kb + 32 * 144 + d0 * 32);
;                 if (d0 == 0) { p0 = __builtin_amdgcn_mfma_f32_32x32x16_bf16(a0, qr[0], zc, 0, 0, 0); p1 = __builtin_amdgcn_mfma_f32_32x32x16_bf16(a1, qr[0], zc, 0, 0, 0); }
;                 else { p0 = __builtin_amdgcn_mfma_f32_32x32x16_bf16(a0, qr[d0], p0, 0, 0, 0); p1 = __builtin_amdgcn_mfma_f32_32x32x16_bf16(a1, qr[d0], p1, 0, 0, 0); }
;             }
;             if (wv < 4) __builtin_amdgcn_s_setprio(0);
.Lew_skip_20760:
	s_or_b32 s0, s18, 1
	s_mul_i32 s1, s0, 0x2400
	v_add_u32_e32 v106, s1, v167
	ds_read_b128 v[102:105], v106
	ds_read_b128 v[110:113], v106 offset:32
	ds_read_b128 v[50:53], v106 offset:4608
	ds_read_b128 v[132:135], v106 offset:4640
	ds_read_b128 v[136:139], v106 offset:64
	ds_read_b128 v[140:143], v106 offset:4672
	ds_read_b128 v[144:147], v106 offset:96
	ds_read_b128 v[148:151], v106 offset:4704
	s_and_b64 vcc, exec, s[8:9]
	s_waitcnt lgkmcnt(7)
	v_mfma_f32_32x32x16_bf16 v[66:81], v[102:105], v[116:119], 0
	s_waitcnt lgkmcnt(6)
	v_mfma_f32_32x32x16_bf16 v[66:81], v[110:113], v[120:123], v[66:81]
	s_waitcnt lgkmcnt(5)
	v_mfma_f32_32x32x16_bf16 v[50:65], v[50:53], v[116:119], 0
	s_waitcnt lgkmcnt(4)
	v_mfma_f32_32x32x16_bf16 v[50:65], v[132:135], v[120:123], v[50:65]
	s_waitcnt lgkmcnt(3)
	v_mfma_f32_32x32x16_bf16 v[66:81], v[136:139], v[124:127], v[66:81]
	s_waitcnt lgkmcnt(2)
	v_mfma_f32_32x32x16_bf16 v[50:65], v[140:143], v[124:127], v[50:65]
	s_waitcnt lgkmcnt(1)
	v_mfma_f32_32x32x16_bf16 v[66:81], v[144:147], v[128:131], v[66:81]
	s_waitcnt lgkmcnt(0)
	v_mfma_f32_32x32x16_bf16 v[50:65], v[148:151], v[128:131], v[50:65]
	s_cbranch_vccnz .LBB0_869
	s_nop 0

; #define LAS __attribute__((address_space(3)))
; template <bool HAS_POST, class MaskF>
; __device__ __forceinline__ void attn_run(LAS unsigned char* lds, const bf16* Kg, const bf16* Vg, int pitch, int t0, int t1,
;                                          const bf16x8 (&qr)[4], f32x16& o0, f32x16& o1, f32x16& o2, MaskF& mf, const int wv) {
;     ...
;             if (wv < 4) __builtin_amdgcn_s_setprio(1);
; #pragma unroll
;             for (int d0 = 0; d0 < 4; ++d0) {
;                 const bf16x8 a0 = *(const LAS bf16x8*)(Kb + d0 * 32), a1 = *(const LAS bf16x8*)(Kb + 32 * 144 + d0 * 32);
;                 if (d0 == 0) { p0 = __builtin_amdgcn_mfma_f32_32x32x16_bf16(a0, qr[0], zc, 0, 0, 0); p1 = __builtin_amdgcn_mfma_f32_32x32x16_bf16(a1, qr[0], zc, 0, 0, 0); }
;                 else { p0 = __builtin_amdgcn_mfma_f32_32x32x16_bf16(a0, qr[d0], p0, 0, 0, 0); p1 = __builtin_amdgcn_mfma_f32_32x32x16_bf16(a1, qr[d0], p1, 0, 0, 0); }
;             }
;             if (wv < 4) __builtin_amdgcn_s_setprio(0);
.LBB0_928:
	s_and_b64 vcc, exec, s[18:19]
	s_waitcnt lgkmcnt(7)
	v_mfma_f32_32x32x16_bf16 v[50:65], v[50:53], v[116:119], 0
	s_waitcnt lgkmcnt(6)
	v_mfma_f32_32x32x16_bf16 v[50:65], v[102:105], v[120:123], v[50:65]
	s_waitcnt lgkmcnt(5)
	v_mfma_f32_32x32x16_bf16 v[66:81], v[66:69], v[116:119], 0
	s_waitcnt lgkmcnt(4)
	v_mfma_f32_32x32x16_bf16 v[66:81], v[106:109], v[120:123], v[66:81]
	s_waitcnt lgkmcnt(3)
	v_mfma_f32_32x32x16_bf16 v[50:65], v[110:113], v[124:127], v[50:65]
	s_waitcnt lgkmcnt(2)
	v_mfma_f32_32x32x16_bf16 v[66:81], v[132:135], v[124:127], v[66:81]
	s_waitcnt lgkmcnt(1)
	v_mfma_f32_32x32x16_bf16 v[50:65], v[136:139], v[128:131], v[50:65]
	s_waitcnt lgkmcnt(0)
	v_mfma_f32_32x32x16_bf16 v[66:81], v[140:143], v[128:131], v[66:81]
	s_cbranch_vccnz .LBB0_930
	s_nop 0

; #define LAS __attribute__((address_space(3)))
; template <bool HAS_POST, class MaskF>
; __device__ __forceinline__ void attn_run(LAS unsigned char* lds, const bf16* Kg, const bf16* Vg, int pitch, int t0, int t1,
;                                          const bf16x8 (&qr)[4], f32x16& o0, f32x16& o1, f32x16& o2, MaskF& mf, const int wv) {
;     ...
;             if (wv < 4) __builtin_amdgcn_s_setprio(1);
; #pragma unroll
;             for (int d0 = 0; d0 < 4; ++d0) {
;                 const bf16x8 a0 = *(const LAS bf16x8*)(Kb + d0 * 32), a1 = *(const LAS bf16x8*)(Kb + 32 * 144 + d0 * 32);
;                 if (d0 == 0) { p0 = __builtin_amdgcn_mfma_f32_32x32x16_bf16(a0, qr[0], zc, 0, 0, 0); p1 = __builtin_amdgcn_mfma_f32_32x32x16_bf16(a1, qr[0], zc, 0, 0, 0); }
;                 else { p0 = __builtin_amdgcn_mfma_f32_32x32x16_bf16(a0, qr[d0], p0, 0, 0, 0); p1 = __builtin_amdgcn_mfma_f32_32x32x16_bf16(a1, qr[d0], p1, 0, 0, 0); }
;             }
;             if (wv < 4) __builtin_amdgcn_s_setprio(0);
.Lew_skip_22585:
	ds_read_b128 v[50:53], v168 offset:9216
	ds_read_b128 v[102:105], v168 offset:9248
	ds_read_b128 v[66:69], v168 offset:13824
	ds_read_b128 v[106:109], v168 offset:13856
	ds_read_b128 v[110:113], v168 offset:9280
	ds_read_b128 v[132:135], v168 offset:13888
	ds_read_b128 v[136:139], v168 offset:9312
	ds_read_b128 v[140:143], v168 offset:13920
	s_and_b64 vcc, exec, s[18:19]
	s_waitcnt lgkmcnt(7)
	v_mfma_f32_32x32x16_bf16 v[50:65], v[50:53], v[116:119], 0
	s_waitcnt lgkmcnt(6)
	v_mfma_f32_32x32x16_bf16 v[50:65], v[102:105], v[120:123], v[50:65]
	s_waitcnt lgkmcnt(5)
	v_mfma_f32_32x32x16_bf16 v[66:81], v[66:69], v[116:119], 0
	s_waitcnt lgkmcnt(4)
	v_mfma_f32_32x32x16_bf16 v[66:81], v[106:109], v[120:123], v[66:81]
	s_waitcnt lgkmcnt(3)
	v_mfma_f32_32x32x16_bf16 v[50:65], v[110:113], v[124:127], v[50:65]
	s_waitcnt lgkmcnt(2)
	v_mfma_f32_32x32x16_bf16 v[66:81], v[132:135], v[124:127], v[66:81]
	s_waitcnt lgkmcnt(1)
	v_mfma_f32_32x32x16_bf16 v[50:65], v[136:139], v[128:131], v[50:65]
	s_waitcnt lgkmcnt(0)
	v_mfma_f32_32x32x16_bf16 v[66:81], v[140:143], v[128:131], v[66:81]
	s_cbranch_vccnz .LBB0_939
	s_nop 0

; #define LAS __attribute__((address_space(3)))
; template <bool HAS_POST, class MaskF>
; __device__ __forceinline__ void attn_run(LAS unsigned char* lds, const bf16* Kg, const bf16* Vg, int pitch, int t0, int t1,
;                                          const bf16x8 (&qr)[4], f32x16& o0, f32x16& o1, f32x16& o2, MaskF& mf, const int wv) {
;     ...
;             if (wv < 4) __builtin_amdgcn_s_setprio(1);
; #pragma unroll
;             for (int d0 = 0; d0 < 4; ++d0) {
;                 const bf16x8 a0 = *(const LAS bf16x8*)(Kb + d0 * 32), a1 = *(const LAS bf16x8*)(Kb + 32 * 144 + d0 * 32);
;                 if (d0 == 0) { p0 = __builtin_amdgcn_mfma_f32_32x32x16_bf16(a0, qr[0], zc, 0, 0, 0); p1 = __builtin_amdgcn_mfma_f32_32x32x16_bf16(a1, qr[0], zc, 0, 0, 0); }
;                 else { p0 = __builtin_amdgcn_mfma_f32_32x32x16_bf16(a0, qr[d0], p0, 0, 0, 0); p1 = __builtin_amdgcn_mfma_f32_32x32x16_bf16(a1, qr[d0], p1, 0, 0, 0); }
;             }
;             if (wv < 4) __builtin_amdgcn_s_setprio(0);
.LBB0_966:
	s_add_i32 s1, s96, -8
	s_and_b32 s97, s1, 2
	s_and_b64 vcc, exec, s[18:19]
	s_waitcnt lgkmcnt(7)
	v_mfma_f32_32x32x16_bf16 v[82:97], v[152:155], v[116:119], 0
	s_waitcnt lgkmcnt(6)
	v_mfma_f32_32x32x16_bf16 v[66:81], v[156:159], v[116:119], 0
	s_waitcnt lgkmcnt(5)
	v_mfma_f32_32x32x16_bf16 v[82:97], v[160:163], v[120:123], v[82:97]
	s_waitcnt lgkmcnt(4)
	v_mfma_f32_32x32x16_bf16 v[66:81], v[164:167], v[120:123], v[66:81]
	s_waitcnt lgkmcnt(3)
	v_mfma_f32_32x32x16_bf16 v[82:97], v[168:171], v[124:127], v[82:97]
	s_waitcnt lgkmcnt(2)
	v_mfma_f32_32x32x16_bf16 v[66:81], v[172:175], v[124:127], v[66:81]
	s_waitcnt lgkmcnt(1)
	v_mfma_f32_32x32x16_bf16 v[82:97], v[176:179], v[128:131], v[82:97]
	s_waitcnt lgkmcnt(0)
	v_mfma_f32_32x32x16_bf16 v[66:81], v[180:183], v[128:131], v[66:81]
	s_cbranch_vccnz .LBB0_968
	s_nop 0

; #define LAS __attribute__((address_space(3)))
; template <bool HAS_POST, class MaskF>
; __device__ __forceinline__ void attn_run(LAS unsigned char* lds, const bf16* Kg, const bf16* Vg, int pitch, int t0, int t1,
;                                          const bf16x8 (&qr)[4], f32x16& o0, f32x16& o1, f32x16& o2, MaskF& mf, const int wv) {
;     ...
;             LAS unsigned char* Kb = lds + (cur * 2 + j) * KBUF + cx.kroff;
;             if (wv < 4) __builtin_amdgcn_s_setprio(1);
; #pragma unroll
;             for (int d0 = 0; d0 < 4; ++d0) {
;                 const bf16x8 a0 = *(const LAS bf16x8*)(Kb + d0 * 32), a1 = *(const LAS bf16x8*)(Kb + 32 * 144 + d0 * 32);
;                 if (d0 == 0) { p0 = __builtin_amdgcn_mfma_f32_32x32x16_bf16(a0, qr[0], zc, 0, 0, 0); p1 = __builtin_amdgcn_mfma_f32_32x32x16_bf16(a1, qr[0], zc, 0, 0, 0); }
;                 else { p0 = __builtin_amdgcn_mfma_f32_32x32x16_bf16(a0, qr[d0], p0, 0, 0, 0); p1 = __builtin_amdgcn_mfma_f32_32x32x16_bf16(a1, qr[d0], p1, 0, 0, 0); }
;             }
;             if (wv < 4) __builtin_amdgcn_s_setprio(0);
.Lew_skip_23466:
	s_or_b32 s0, s97, 1
	s_mul_i32 s1, s0, 0x2400
	v_add_u32_e32 v86, s1, v207
	ds_read_b128 v[152:155], v86
	ds_read_b128 v[156:159], v86 offset:32
	ds_read_b128 v[50:53], v86 offset:4608
	ds_read_b128 v[160:163], v86 offset:4640
	ds_read_b128 v[164:167], v86 offset:64
	ds_read_b128 v[168:171], v86 offset:4672
	ds_read_b128 v[172:175], v86 offset:96
	ds_read_b128 v[176:179], v86 offset:4704
	s_and_b64 vcc, exec, s[18:19]
	s_waitcnt lgkmcnt(7)
	v_mfma_f32_32x32x16_bf16 v[66:81], v[152:155], v[116:119], 0
	s_waitcnt lgkmcnt(6)
	v_mfma_f32_32x32x16_bf16 v[66:81], v[156:159], v[120:123], v[66:81]
	s_waitcnt lgkmcnt(5)
	v_mfma_f32_32x32x16_bf16 v[50:65], v[50:53], v[116:119], 0
	s_waitcnt lgkmcnt(4)
	v_mfma_f32_32x32x16_bf16 v[50:65], v[160:163], v[120:123], v[50:65]
	s_waitcnt lgkmcnt(3)
	v_mfma_f32_32x32x16_bf16 v[66:81], v[164:167], v[124:127], v[66:81]
	s_waitcnt lgkmcnt(2)
	v_mfma_f32_32x32x16_bf16 v[50:65], v[168:171], v[124:127], v[50:65]
	s_waitcnt lgkmcnt(1)
	v_mfma_f32_32x32x16_bf16 v[66:81], v[172:175], v[128:131], v[66:81]
	s_waitcnt lgkmcnt(0)
	v_mfma_f32_32x32x16_bf16 v[50:65], v[176:179], v[128:131], v[50:65]
	s_cbranch_vccnz .LBB0_981
	s_nop 0

; #define LAS __attribute__((address_space(3)))
; template <bool HAS_POST, class MaskF>
; __device__ __forceinline__ void attn_run(LAS unsigned char* lds, const bf16* Kg, const bf16* Vg, int pitch, int t0, int t1,
;                                          const bf16x8 (&qr)[4], f32x16& o0, f32x16& o1, f32x16& o2, MaskF& mf, const int wv) {
;     ...
;             LAS unsigned char* Kb = lds + (cur * 2 + j) * KBUF + cx.kroff;
;             if (wv < 4) __builtin_amdgcn_s_setprio(1);
; #pragma unroll
;             for (int d0 = 0; d0 < 4; ++d0) {
;                 const bf16x8 a0 = *(const LAS bf16x8*)(Kb + d0 * 32), a1 = *(const LAS bf16x8*)(Kb + 32 * 144 + d0 * 32);
;                 if (d0 == 0) { p0 = __builtin_amdgcn_mfma_f32_32x32x16_bf16(a0, qr[0], zc, 0, 0, 0); p1 = __builtin_amdgcn_mfma_f32_32x32x16_bf16(a1, qr[0], zc, 0, 0, 0); }
;                 else { p0 = __builtin_amdgcn_mfma_f32_32x32x16_bf16(a0, qr[d0], p0, 0, 0, 0); p1 = __builtin_amdgcn_mfma_f32_32x32x16_bf16(a1, qr[d0], p1, 0, 0, 0); }
;             }
;             if (wv < 4) __builtin_amdgcn_s_setprio(0);
.LBB0_1175:
	s_mul_i32 s1, s59, 0x2400
	s_and_b64 vcc, exec, s[8:9]
	s_waitcnt lgkmcnt(7)
	v_mfma_f32_32x32x16_bf16 v[64:79], v[120:123], v[80:83], 0
	s_waitcnt lgkmcnt(6)
	v_mfma_f32_32x32x16_bf16 v[64:79], v[128:131], v[84:87], v[64:79]
	s_waitcnt lgkmcnt(5)
	v_mfma_f32_32x32x16_bf16 v[48:63], v[176:179], v[80:83], 0
	s_waitcnt lgkmcnt(4)
	v_mfma_f32_32x32x16_bf16 v[48:63], v[132:135], v[84:87], v[48:63]
	s_waitcnt lgkmcnt(3)
	v_mfma_f32_32x32x16_bf16 v[64:79], v[136:139], v[88:91], v[64:79]
	s_waitcnt lgkmcnt(2)
	v_mfma_f32_32x32x16_bf16 v[48:63], v[140:143], v[88:91], v[48:63]
	s_waitcnt lgkmcnt(1)
	v_mfma_f32_32x32x16_bf16 v[64:79], v[144:147], v[92:95], v[64:79]
	s_waitcnt lgkmcnt(0)
	v_mfma_f32_32x32x16_bf16 v[48:63], v[148:151], v[92:95], v[48:63]
	s_cbranch_vccnz .LBB0_1177
	s_nop 0

; #define LAS __attribute__((address_space(3)))
; template <bool HAS_POST, class MaskF>
; __device__ __forceinline__ void attn_run(LAS unsigned char* lds, const bf16* Kg, const bf16* Vg, int pitch, int t0, int t1,
;                                          const bf16x8 (&qr)[4], f32x16& o0, f32x16& o1, f32x16& o2, MaskF& mf, const int wv) {
;     ...
;             LAS unsigned char* Kb = lds + (cur * 2 + j) * KBUF + cx.kroff;
;             if (wv < 4) __builtin_amdgcn_s_setprio(1);
; #pragma unroll
;             for (int d0 = 0; d0 < 4; ++d0) {
;                 const bf16x8 a0 = *(const LAS bf16x8*)(Kb + d0 * 32), a1 = *(const LAS bf16x8*)(Kb + 32 * 144 + d0 * 32);
;                 if (d0 == 0) { p0 = __builtin_amdgcn_mfma_f32_32x32x16_bf16(a0, qr[0], zc, 0, 0, 0); p1 = __builtin_amdgcn_mfma_f32_32x32x16_bf16(a1, qr[0], zc, 0, 0, 0); }
;                 else { p0 = __builtin_amdgcn_mfma_f32_32x32x16_bf16(a0, qr[d0], p0, 0, 0, 0); p1 = __builtin_amdgcn_mfma_f32_32x32x16_bf16(a1, qr[d0], p1, 0, 0, 0); }
;             }
;             if (wv < 4) __builtin_amdgcn_s_setprio(0);
.Lew_skip_29169:
	s_or_b32 s0, s59, 1
	s_mul_i32 s1, s0, 0x2400
	v_add_u32_e32 v124, s1, v165
	ds_read_b128 v[48:51], v124
	ds_read_b128 v[120:123], v124 offset:32
	ds_read_b128 v[64:67], v124 offset:4608
	ds_read_b128 v[128:131], v124 offset:4640
	ds_read_b128 v[132:135], v124 offset:64
	ds_read_b128 v[136:139], v124 offset:4672
	ds_read_b128 v[140:143], v124 offset:96
	ds_read_b128 v[144:147], v124 offset:4704
	s_and_b64 vcc, exec, s[10:11]
	s_waitcnt lgkmcnt(7)
	v_mfma_f32_32x32x16_bf16 v[48:63], v[48:51], v[80:83], 0
	s_waitcnt lgkmcnt(6)
	v_mfma_f32_32x32x16_bf16 v[48:63], v[120:123], v[84:87], v[48:63]
	s_waitcnt lgkmcnt(5)
	v_mfma_f32_32x32x16_bf16 v[64:79], v[64:67], v[80:83], 0
	s_waitcnt lgkmcnt(4)
	v_mfma_f32_32x32x16_bf16 v[64:79], v[128:131], v[84:87], v[64:79]
	s_waitcnt lgkmcnt(3)
	v_mfma_f32_32x32x16_bf16 v[48:63], v[132:135], v[88:91], v[48:63]
	s_waitcnt lgkmcnt(2)
	v_mfma_f32_32x32x16_bf16 v[64:79], v[136:139], v[88:91], v[64:79]
	s_waitcnt lgkmcnt(1)
	v_mfma_f32_32x32x16_bf16 v[48:63], v[140:143], v[92:95], v[48:63]
	s_waitcnt lgkmcnt(0)
	v_mfma_f32_32x32x16_bf16 v[64:79], v[144:147], v[92:95], v[64:79]
	s_cbranch_vccnz .LBB0_1196
	s_nop 0
